# hf1 4th gate quad moved to contiguous v[180:183]: x4 load/store instead of 2 x2 (producer 5+5 -> 4+4 VMEM ops), waits 56/56
# speedup vs baseline: 1.0125x; 1.0056x over previous
.LBB0_295:
	ds_read_b128 v[130:133], v188
	ds_read_b128 v[134:137], v188 offset:16
	ds_read_b128 v[138:141], v188 offset:256
	ds_read_b128 v[142:145], v188 offset:272
	ds_read_b128 v[146:149], v188 offset:512
	ds_read_b128 v[150:153], v188 offset:528
	ds_read_b128 v[154:157], v188 offset:768
	ds_read_b128 v[166:169], v188 offset:784
	s_sub_i32 s0, s8, s25
	v_cmp_gt_i32_e32 vcc, s26, v175
	s_min_i32 s1, s24, s20
	s_lshl_b32 s1, s1, 5
	s_sub_i32 s25, s17, s1
	v_lshlrev_b32_e32 v172, 16, v126
	v_and_b32_e32 v173, 0xffff0000, v126
	s_cmp_gt_i32 s25, 31
	s_waitcnt lgkmcnt(6)
	v_mul_f32_e32 v238, v130, v130
	v_mul_f32_e32 v239, v131, v131
	v_mul_f32_e32 v240, v132, v132
	v_mul_f32_e32 v241, v133, v133
	v_fmac_f32_e32 v238, v134, v134
	v_fmac_f32_e32 v239, v135, v135
	v_fmac_f32_e32 v240, v136, v136
	v_fmac_f32_e32 v241, v137, v137
	s_waitcnt lgkmcnt(4)
	v_fmac_f32_e32 v238, v138, v138
	v_fmac_f32_e32 v239, v139, v139
	v_fmac_f32_e32 v240, v140, v140
	v_fmac_f32_e32 v241, v141, v141
	v_fmac_f32_e32 v238, v142, v142
	v_fmac_f32_e32 v239, v143, v143
	v_fmac_f32_e32 v240, v144, v144
	v_fmac_f32_e32 v241, v145, v145
	s_waitcnt lgkmcnt(2)
	v_fmac_f32_e32 v238, v146, v146
	v_fmac_f32_e32 v239, v147, v147
	v_fmac_f32_e32 v240, v148, v148
	v_fmac_f32_e32 v241, v149, v149
	v_fmac_f32_e32 v238, v150, v150
	v_fmac_f32_e32 v239, v151, v151
	v_fmac_f32_e32 v240, v152, v152
	v_fmac_f32_e32 v241, v153, v153
	s_waitcnt lgkmcnt(0)
	v_fmac_f32_e32 v238, v154, v154
	v_fmac_f32_e32 v239, v155, v155
	v_fmac_f32_e32 v240, v156, v156
	v_fmac_f32_e32 v241, v157, v157
	v_fmac_f32_e32 v238, v166, v166
	v_fmac_f32_e32 v239, v167, v167
	v_fmac_f32_e32 v240, v168, v168
	v_fmac_f32_e32 v241, v169, v169
	v_add_f32_e32 v238, v238, v239
	v_add_f32_e32 v240, v240, v241
	v_add_f32_e32 v158, v238, v240
	s_nop 1
	v_add_f32_dpp v158, v158, v158 quad_perm:[1,0,3,2] row_mask:0xf bank_mask:0xf
	s_nop 1
	v_add_f32_dpp v158, v158, v158 quad_perm:[2,3,0,1] row_mask:0xf bank_mask:0xf
	s_nop 1
	v_add_f32_dpp v158, v158, v158 row_half_mirror row_mask:0xf bank_mask:0xf
	v_fmamk_f32 v158, v158, 0x3b800000, v206
	v_rsq_f32_e32 v158, v158
	s_waitcnt vmcnt(56)
	v_mov_b32_e32 v159, s0
	v_cndmask_b32_e32 v159, v210, v159, vcc
	v_add_u32_e32 v170, v159, v175
	v_ashrrev_i32_e32 v171, 31, v170
	v_lshlrev_b64 v[170:171], 13, v[170:171]
	v_lshl_add_u64 v[170:171], v[74:75], 0, v[170:171]
	v_pk_mul_f32 v[130:131], v[130:131], v[158:159] op_sel_hi:[1,0]
	v_lshlrev_b32_e32 v238, 16, v80
	v_and_b32_e32 v239, 0xffff0000, v80
	v_pk_mul_f32 v[130:131], v[130:131], v[238:239]
	v_cvt_pk_bf16_f32 v80, v130, v131
	v_pk_mul_f32 v[132:133], v[132:133], v[158:159] op_sel_hi:[1,0]
	v_lshlrev_b32_e32 v238, 16, v81
	v_and_b32_e32 v239, 0xffff0000, v81
	v_pk_mul_f32 v[132:133], v[132:133], v[238:239]
	v_cvt_pk_bf16_f32 v81, v132, v133
	v_pk_mul_f32 v[134:135], v[134:135], v[158:159] op_sel_hi:[1,0]
	v_lshlrev_b32_e32 v238, 16, v82
	v_and_b32_e32 v239, 0xffff0000, v82
	v_pk_mul_f32 v[134:135], v[134:135], v[238:239]
	v_cvt_pk_bf16_f32 v82, v134, v135
	v_pk_mul_f32 v[136:137], v[136:137], v[158:159] op_sel_hi:[1,0]
	v_lshlrev_b32_e32 v238, 16, v83
	v_and_b32_e32 v239, 0xffff0000, v83
	v_pk_mul_f32 v[136:137], v[136:137], v[238:239]
	v_cvt_pk_bf16_f32 v83, v136, v137
	global_store_dwordx4 v[170:171], v[80:83], off
	v_pk_mul_f32 v[138:139], v[138:139], v[158:159] op_sel_hi:[1,0]
	v_lshlrev_b32_e32 v238, 16, v84
	v_and_b32_e32 v239, 0xffff0000, v84
	v_pk_mul_f32 v[138:139], v[138:139], v[238:239]
	v_cvt_pk_bf16_f32 v84, v138, v139
	v_pk_mul_f32 v[140:141], v[140:141], v[158:159] op_sel_hi:[1,0]
	v_lshlrev_b32_e32 v238, 16, v85
	v_and_b32_e32 v239, 0xffff0000, v85
	v_pk_mul_f32 v[140:141], v[140:141], v[238:239]
	v_cvt_pk_bf16_f32 v85, v140, v141
	v_pk_mul_f32 v[142:143], v[142:143], v[158:159] op_sel_hi:[1,0]
	v_lshlrev_b32_e32 v238, 16, v86
	v_and_b32_e32 v239, 0xffff0000, v86
	v_pk_mul_f32 v[142:143], v[142:143], v[238:239]
	v_cvt_pk_bf16_f32 v86, v142, v143
	v_pk_mul_f32 v[144:145], v[144:145], v[158:159] op_sel_hi:[1,0]
	v_lshlrev_b32_e32 v238, 16, v87
	v_and_b32_e32 v239, 0xffff0000, v87
	v_pk_mul_f32 v[144:145], v[144:145], v[238:239]
	v_cvt_pk_bf16_f32 v87, v144, v145
	global_store_dwordx4 v[170:171], v[84:87], off offset:128
	v_pk_mul_f32 v[146:147], v[146:147], v[158:159] op_sel_hi:[1,0]
	v_lshlrev_b32_e32 v238, 16, v92
	v_and_b32_e32 v239, 0xffff0000, v92
	v_pk_mul_f32 v[146:147], v[146:147], v[238:239]
	v_cvt_pk_bf16_f32 v92, v146, v147
	v_pk_mul_f32 v[148:149], v[148:149], v[158:159] op_sel_hi:[1,0]
	v_lshlrev_b32_e32 v238, 16, v93
	v_and_b32_e32 v239, 0xffff0000, v93
	v_pk_mul_f32 v[148:149], v[148:149], v[238:239]
	v_cvt_pk_bf16_f32 v93, v148, v149
	v_pk_mul_f32 v[150:151], v[150:151], v[158:159] op_sel_hi:[1,0]
	v_lshlrev_b32_e32 v238, 16, v94
	v_and_b32_e32 v239, 0xffff0000, v94
	v_pk_mul_f32 v[150:151], v[150:151], v[238:239]
	v_cvt_pk_bf16_f32 v94, v150, v151
	v_pk_mul_f32 v[152:153], v[152:153], v[158:159] op_sel_hi:[1,0]
	v_lshlrev_b32_e32 v238, 16, v95
	v_and_b32_e32 v239, 0xffff0000, v95
	v_pk_mul_f32 v[152:153], v[152:153], v[238:239]
	v_cvt_pk_bf16_f32 v95, v152, v153
	global_store_dwordx4 v[170:171], v[92:95], off offset:256
	v_pk_mul_f32 v[154:155], v[154:155], v[158:159] op_sel_hi:[1,0]
	v_lshlrev_b32_e32 v238, 16, v96
	v_and_b32_e32 v239, 0xffff0000, v96
	v_pk_mul_f32 v[154:155], v[154:155], v[238:239]
	v_cvt_pk_bf16_f32 v96, v154, v155
	v_pk_mul_f32 v[156:157], v[156:157], v[158:159] op_sel_hi:[1,0]
	v_lshlrev_b32_e32 v238, 16, v97
	v_and_b32_e32 v239, 0xffff0000, v97
	v_pk_mul_f32 v[156:157], v[156:157], v[238:239]
	v_cvt_pk_bf16_f32 v97, v156, v157
	v_pk_mul_f32 v[166:167], v[166:167], v[158:159] op_sel_hi:[1,0]
	v_lshlrev_b32_e32 v238, 16, v98
	v_and_b32_e32 v239, 0xffff0000, v98
	v_pk_mul_f32 v[166:167], v[166:167], v[238:239]
	v_cvt_pk_bf16_f32 v98, v166, v167
	v_pk_mul_f32 v[168:169], v[168:169], v[158:159] op_sel_hi:[1,0]
	v_lshlrev_b32_e32 v238, 16, v99
	v_and_b32_e32 v239, 0xffff0000, v99
	v_pk_mul_f32 v[168:169], v[168:169], v[238:239]
	v_cvt_pk_bf16_f32 v99, v168, v169
	global_store_dwordx4 v[170:171], v[96:99], off offset:384
	s_waitcnt vmcnt(4)
	v_lshlrev_b32_e32 v168, 16, v232
	v_add_u32_e32 v238, s1, v217
	v_ashrrev_i32_e32 v239, 31, v238
	v_lshlrev_b64 v[238:239], 13, v[238:239]
	v_lshl_add_u64 v[238:239], v[78:79], 0, v[238:239]
	global_load_dwordx4 v[80:83], v[238:239], off
	global_load_dwordx4 v[84:87], v[238:239], off offset:128
	global_load_dwordx4 v[92:95], v[238:239], off offset:256
	global_load_dwordx4 v[96:99], v[238:239], off offset:384
	s_cmp_lt_u32 s24, s18
	s_cbranch_scc1 .Lscan_tl_n0
	s_add_i32 s25, s24, 2
	s_mov_b64 s[0:1], exec
	s_waitcnt vmcnt(0)
	s_branch .LBB0_301

.LBB0_305:
	ds_read_b128 v[130:133], v188 offset:33280
	ds_read_b128 v[134:137], v188 offset:33296
	ds_read_b128 v[138:141], v188 offset:33536
	ds_read_b128 v[142:145], v188 offset:33552
	ds_read_b128 v[146:149], v188 offset:33792
	ds_read_b128 v[150:153], v188 offset:33808
	ds_read_b128 v[154:157], v188 offset:34048
	ds_read_b128 v[166:169], v188 offset:34064
	s_sub_i32 s0, s21, s0
	v_cmp_gt_i32_e32 vcc, s1, v175
	s_add_i32 s10, s24, 1
	s_min_i32 s10, s10, s20
	v_lshlrev_b32_e32 v170, 16, v124
	v_and_b32_e32 v171, 0xffff0000, v124
	s_lshl_b32 s10, s10, 5
	s_waitcnt lgkmcnt(6)
	v_mul_f32_e32 v238, v130, v130
	v_mul_f32_e32 v239, v131, v131
	v_mul_f32_e32 v240, v132, v132
	v_mul_f32_e32 v241, v133, v133
	v_fmac_f32_e32 v238, v134, v134
	v_fmac_f32_e32 v239, v135, v135
	v_fmac_f32_e32 v240, v136, v136
	v_fmac_f32_e32 v241, v137, v137
	s_waitcnt lgkmcnt(4)
	v_fmac_f32_e32 v238, v138, v138
	v_fmac_f32_e32 v239, v139, v139
	v_fmac_f32_e32 v240, v140, v140
	v_fmac_f32_e32 v241, v141, v141
	v_fmac_f32_e32 v238, v142, v142
	v_fmac_f32_e32 v239, v143, v143
	v_fmac_f32_e32 v240, v144, v144
	v_fmac_f32_e32 v241, v145, v145
	s_waitcnt lgkmcnt(2)
	v_fmac_f32_e32 v238, v146, v146
	v_fmac_f32_e32 v239, v147, v147
	v_fmac_f32_e32 v240, v148, v148
	v_fmac_f32_e32 v241, v149, v149
	v_fmac_f32_e32 v238, v150, v150
	v_fmac_f32_e32 v239, v151, v151
	v_fmac_f32_e32 v240, v152, v152
	v_fmac_f32_e32 v241, v153, v153
	s_waitcnt lgkmcnt(0)
	v_fmac_f32_e32 v238, v154, v154
	v_fmac_f32_e32 v239, v155, v155
	v_fmac_f32_e32 v240, v156, v156
	v_fmac_f32_e32 v241, v157, v157
	v_fmac_f32_e32 v238, v166, v166
	v_fmac_f32_e32 v239, v167, v167
	v_fmac_f32_e32 v240, v168, v168
	v_fmac_f32_e32 v241, v169, v169
	v_add_f32_e32 v238, v238, v239
	v_add_f32_e32 v240, v240, v241
	v_add_f32_e32 v158, v238, v240
	s_nop 1
	v_add_f32_dpp v158, v158, v158 quad_perm:[1,0,3,2] row_mask:0xf bank_mask:0xf
	s_nop 1
	v_add_f32_dpp v158, v158, v158 quad_perm:[2,3,0,1] row_mask:0xf bank_mask:0xf
	s_nop 1
	v_add_f32_dpp v158, v158, v158 row_half_mirror row_mask:0xf bank_mask:0xf
	v_fmamk_f32 v158, v158, 0x3b800000, v206
	v_rsq_f32_e32 v158, v158
	s_waitcnt vmcnt(56)
	v_mov_b32_e32 v159, s0
	v_cndmask_b32_e32 v159, v210, v159, vcc
	v_add_u32_e32 v162, v159, v175
	v_ashrrev_i32_e32 v163, 31, v162
	v_lshlrev_b64 v[162:163], 13, v[162:163]
	v_lshl_add_u64 v[162:163], v[74:75], 0, v[162:163]
	s_mov_b64 s[0:1], -1
	v_pk_mul_f32 v[130:131], v[130:131], v[158:159] op_sel_hi:[1,0]
	v_lshlrev_b32_e32 v238, 16, v120
	v_and_b32_e32 v239, 0xffff0000, v120
	v_pk_mul_f32 v[130:131], v[130:131], v[238:239]
	v_cvt_pk_bf16_f32 v120, v130, v131
	v_pk_mul_f32 v[132:133], v[132:133], v[158:159] op_sel_hi:[1,0]
	v_lshlrev_b32_e32 v238, 16, v121
	v_and_b32_e32 v239, 0xffff0000, v121
	v_pk_mul_f32 v[132:133], v[132:133], v[238:239]
	v_cvt_pk_bf16_f32 v121, v132, v133
	v_pk_mul_f32 v[134:135], v[134:135], v[158:159] op_sel_hi:[1,0]
	v_lshlrev_b32_e32 v238, 16, v122
	v_and_b32_e32 v239, 0xffff0000, v122
	v_pk_mul_f32 v[134:135], v[134:135], v[238:239]
	v_cvt_pk_bf16_f32 v122, v134, v135
	v_pk_mul_f32 v[136:137], v[136:137], v[158:159] op_sel_hi:[1,0]
	v_lshlrev_b32_e32 v238, 16, v123
	v_and_b32_e32 v239, 0xffff0000, v123
	v_pk_mul_f32 v[136:137], v[136:137], v[238:239]
	v_cvt_pk_bf16_f32 v123, v136, v137
	global_store_dwordx4 v[162:163], v[120:123], off
	v_pk_mul_f32 v[138:139], v[138:139], v[158:159] op_sel_hi:[1,0]
	v_lshlrev_b32_e32 v238, 16, v124
	v_and_b32_e32 v239, 0xffff0000, v124
	v_pk_mul_f32 v[138:139], v[138:139], v[238:239]
	v_cvt_pk_bf16_f32 v124, v138, v139
	v_pk_mul_f32 v[140:141], v[140:141], v[158:159] op_sel_hi:[1,0]
	v_lshlrev_b32_e32 v238, 16, v125
	v_and_b32_e32 v239, 0xffff0000, v125
	v_pk_mul_f32 v[140:141], v[140:141], v[238:239]
	v_cvt_pk_bf16_f32 v125, v140, v141
	v_pk_mul_f32 v[142:143], v[142:143], v[158:159] op_sel_hi:[1,0]
	v_lshlrev_b32_e32 v238, 16, v126
	v_and_b32_e32 v239, 0xffff0000, v126
	v_pk_mul_f32 v[142:143], v[142:143], v[238:239]
	v_cvt_pk_bf16_f32 v126, v142, v143
	v_pk_mul_f32 v[144:145], v[144:145], v[158:159] op_sel_hi:[1,0]
	v_lshlrev_b32_e32 v238, 16, v127
	v_and_b32_e32 v239, 0xffff0000, v127
	v_pk_mul_f32 v[144:145], v[144:145], v[238:239]
	v_cvt_pk_bf16_f32 v127, v144, v145
	global_store_dwordx4 v[162:163], v[124:127], off offset:128
	v_pk_mul_f32 v[146:147], v[146:147], v[158:159] op_sel_hi:[1,0]
	v_lshlrev_b32_e32 v238, 16, v110
	v_and_b32_e32 v239, 0xffff0000, v110
	v_pk_mul_f32 v[146:147], v[146:147], v[238:239]
	v_cvt_pk_bf16_f32 v110, v146, v147
	v_pk_mul_f32 v[148:149], v[148:149], v[158:159] op_sel_hi:[1,0]
	v_lshlrev_b32_e32 v238, 16, v111
	v_and_b32_e32 v239, 0xffff0000, v111
	v_pk_mul_f32 v[148:149], v[148:149], v[238:239]
	v_cvt_pk_bf16_f32 v111, v148, v149
	v_pk_mul_f32 v[150:151], v[150:151], v[158:159] op_sel_hi:[1,0]
	v_lshlrev_b32_e32 v238, 16, v112
	v_and_b32_e32 v239, 0xffff0000, v112
	v_pk_mul_f32 v[150:151], v[150:151], v[238:239]
	v_cvt_pk_bf16_f32 v112, v150, v151
	v_pk_mul_f32 v[152:153], v[152:153], v[158:159] op_sel_hi:[1,0]
	v_lshlrev_b32_e32 v238, 16, v113
	v_and_b32_e32 v239, 0xffff0000, v113
	v_pk_mul_f32 v[152:153], v[152:153], v[238:239]
	v_cvt_pk_bf16_f32 v113, v152, v153
	global_store_dwordx4 v[162:163], v[110:113], off offset:256
	v_pk_mul_f32 v[154:155], v[154:155], v[158:159] op_sel_hi:[1,0]
	v_lshlrev_b32_e32 v238, 16, v180
	v_and_b32_e32 v239, 0xffff0000, v180
	v_pk_mul_f32 v[154:155], v[154:155], v[238:239]
	v_cvt_pk_bf16_f32 v180, v154, v155
	v_pk_mul_f32 v[156:157], v[156:157], v[158:159] op_sel_hi:[1,0]
	v_lshlrev_b32_e32 v238, 16, v181
	v_and_b32_e32 v239, 0xffff0000, v181
	v_pk_mul_f32 v[156:157], v[156:157], v[238:239]
	v_cvt_pk_bf16_f32 v181, v156, v157
	v_pk_mul_f32 v[166:167], v[166:167], v[158:159] op_sel_hi:[1,0]
	v_lshlrev_b32_e32 v238, 16, v182
	v_and_b32_e32 v239, 0xffff0000, v182
	v_pk_mul_f32 v[166:167], v[166:167], v[238:239]
	v_cvt_pk_bf16_f32 v182, v166, v167
	v_pk_mul_f32 v[168:169], v[168:169], v[158:159] op_sel_hi:[1,0]
	v_lshlrev_b32_e32 v238, 16, v183
	v_and_b32_e32 v239, 0xffff0000, v183
	v_pk_mul_f32 v[168:169], v[168:169], v[238:239]
	v_cvt_pk_bf16_f32 v183, v168, v169
	global_store_dwordx4 v[162:163], v[180:183], off offset:384
	v_add_u32_e32 v238, s10, v217
	v_ashrrev_i32_e32 v239, 31, v238
	v_lshlrev_b64 v[238:239], 13, v[238:239]
	v_lshl_add_u64 v[238:239], v[78:79], 0, v[238:239]
	global_load_dwordx4 v[120:123], v[238:239], off
	global_load_dwordx4 v[124:127], v[238:239], off offset:128
	global_load_dwordx4 v[110:113], v[238:239], off offset:256
	global_load_dwordx4 v[180:183], v[238:239], off offset:384
	s_add_i32 s98, s24, 1
	s_cmp_lt_u32 s98, s18
	s_cbranch_scc1 .Lscan_tl_n1
	s_mov_b64 s[0:1], exec
	s_waitcnt vmcnt(0)
	s_branch .LBB0_290
